# final RMSNorm: gain vector loaded once per wave instead of four dependent loads per token
# baseline (speedup 1.0000x reference)
; __device__ __forceinline__ int get_tid() { int t = threadIdx.x; asm volatile("" : "+v"(t)); return t; }
; __device__ __forceinline__ int get_bid() { int b = blockIdx.x; asm volatile("" : "+s"(b)); return b; }
; __device__ __forceinline__ void final_norm_token(const Params& p, int t, int lane) {
;     float* xr = p.out + (size_t)t * 1024;
;     f32x4 v[4];
; #pragma unroll
;     for (int i = 0; i < 4; ++i) v[i] = *(const f32x4*)(xr + i * 256 + lane * 4);
;     float ss = 0.f;
; #pragma unroll
;     for (int i = 0; i < 4; ++i) ss += v[i][0] * v[i][0] + v[i][1] * v[i][1] + v[i][2] * v[i][2] + v[i][3] * v[i][3];
;     ss = wave_sum(ss);
;     const float r = rsqrtf(ss * (1.0f / 1024.0f) + EPS);
; #pragma unroll
;     for (int i = 0; i < 4; ++i) { const f32x4 gg = *(const f32x4*)(p.final_g + i * 256 + lane * 4); *(f32x4*)(xr + i * 256 + lane * 4) = v[i] * r * gg; }
; }
; __device__ void run_phase(const Params& p, int ph, char* smem) {
;     ...
;         const int tid = get_tid(), wid = __builtin_amdgcn_readfirstlane(tid >> 6), lane = tid & 63;
;         for (int t = get_bid() * 4 + wid; t < T; t += gridDim.x * 4) final_norm_token(p, t, lane);
.LBB0_15:
	s_cmp_eq_u32 s8, 19
	s_mov_b64 s[22:23], -1
	s_cbranch_scc0 .LBB0_20
	v_mov_b32_e32 v0, v126
	s_mov_b32 s10, s2
	s_lshl_b32 s10, s10, 2
	v_readfirstlane_b32 s9, v0
	s_ashr_i32 s9, s9, 6
	s_add_i32 s22, s10, s9
	s_cmpk_gt_i32 s22, 0x7fff
	v_readlane_b32 s8, v167, 15
	s_mov_b32 s7, 0x800000
	s_waitcnt lgkmcnt(0)
	v_mov_b32_e32 v33, 0x358637bd
	s_cbranch_scc1 .LBB0_19
	v_cmp_lt_i32_e32 vcc, v133, v132
	v_lshlrev_b32_e32 v0, 4, v0
	v_and_b32_e32 v112, 0x3f0, v0
	v_cndmask_b32_e32 v1, v130, v133, vcc
	v_cmp_lt_i32_e32 vcc, v134, v132
	v_lshlrev_b32_e32 v27, 2, v1
	v_lshl_add_u64 v[20:21], s[82:83], 0, v[112:113]
	v_cndmask_b32_e32 v1, v130, v134, vcc
	v_cmp_lt_i32_e32 vcc, v125, v132
	v_lshlrev_b32_e32 v28, 2, v1
	v_lshl_add_u64 v[22:23], s[80:81], 0, v[112:113]
	v_cndmask_b32_e32 v1, v130, v125, vcc
	v_cmp_lt_i32_e32 vcc, v127, v132
	v_lshlrev_b32_e32 v29, 2, v1
	s_nop 0
	v_cndmask_b32_e32 v1, v130, v127, vcc
	v_cmp_lt_i32_e32 vcc, v128, v132
	v_lshlrev_b32_e32 v30, 2, v1
	s_nop 0
	v_cndmask_b32_e32 v1, v130, v128, vcc
	v_cmp_lt_i32_e32 vcc, v129, v132
	v_lshlrev_b32_e32 v31, 2, v1
	s_nop 0
	v_cndmask_b32_e32 v1, v130, v129, vcc
	v_lshlrev_b32_e32 v32, 2, v1
	global_load_dwordx4 v[36:39], v[22:23], off
	global_load_dwordx4 v[40:43], v[22:23], off offset:1024
	global_load_dwordx4 v[44:47], v[22:23], off offset:2048
	global_load_dwordx4 v[48:51], v[22:23], off offset:3072
.LBB0_18:
	s_ashr_i32 s23, s22, 31
	s_lshl_b64 s[10:11], s[22:23], 12
	v_lshl_add_u64 v[24:25], v[20:21], 0, s[10:11]
	global_load_dwordx4 v[12:15], v[24:25], off
	global_load_dwordx4 v[8:11], v[24:25], off offset:1024
	global_load_dwordx4 v[4:7], v[24:25], off offset:2048
	global_load_dwordx4 v[0:3], v[24:25], off offset:3072
	s_add_i32 s22, s22, s8
	s_cmpk_gt_i32 s22, 0x7fff
	s_waitcnt vmcnt(3)
	v_mov_b32_e32 v18, v13
	s_waitcnt vmcnt(2)
	v_mov_b32_e32 v19, v9
	v_mov_b32_e32 v16, v12
	v_mov_b32_e32 v17, v8
	v_pk_mul_f32 v[18:19], v[18:19], v[18:19]
	s_waitcnt vmcnt(1)
	v_mov_b32_e32 v34, v5
	v_pk_fma_f32 v[16:17], v[16:17], v[16:17], v[18:19]
	v_mov_b32_e32 v18, v14
	v_mov_b32_e32 v19, v10
	v_pk_fma_f32 v[16:17], v[18:19], v[18:19], v[16:17]
	v_mov_b32_e32 v18, v15
	v_mov_b32_e32 v19, v11
	s_waitcnt vmcnt(0)
	v_mov_b32_e32 v35, v1
	v_pk_fma_f32 v[16:17], v[18:19], v[18:19], v[16:17]
	v_mov_b32_e32 v18, v4
	v_mov_b32_e32 v19, v0
	v_pk_mul_f32 v[34:35], v[34:35], v[34:35]
	v_add_f32_e32 v16, v16, v17
	v_pk_fma_f32 v[18:19], v[18:19], v[18:19], v[34:35]
	v_mov_b32_e32 v34, v6
	v_mov_b32_e32 v35, v2
	v_pk_fma_f32 v[18:19], v[34:35], v[34:35], v[18:19]
	v_mov_b32_e32 v34, v7
	v_mov_b32_e32 v35, v3
	v_pk_fma_f32 v[18:19], v[34:35], v[34:35], v[18:19]
	s_nop 0
	v_add_f32_e32 v16, v16, v18
	v_add_f32_e32 v16, v16, v19
	ds_bpermute_b32 v17, v27, v16
	s_waitcnt lgkmcnt(0)
	v_add_f32_e32 v16, v16, v17
	ds_bpermute_b32 v17, v28, v16
	s_waitcnt lgkmcnt(0)
	v_add_f32_e32 v16, v16, v17
	ds_bpermute_b32 v17, v29, v16
	s_waitcnt lgkmcnt(0)
	v_add_f32_e32 v16, v16, v17
	ds_bpermute_b32 v17, v30, v16
	s_waitcnt lgkmcnt(0)
	v_add_f32_e32 v16, v16, v17
	ds_bpermute_b32 v17, v31, v16
	s_waitcnt lgkmcnt(0)
	v_add_f32_e32 v16, v16, v17
	ds_bpermute_b32 v17, v32, v16
	s_waitcnt lgkmcnt(0)
	v_add_f32_e32 v16, v16, v17
	v_fmamk_f32 v16, v16, 0x3a800000, v33
	v_cmp_gt_f32_e32 vcc, s7, v16
	v_mul_f32_e32 v17, 0x4b800000, v16
	s_nop 0
	v_cndmask_b32_e32 v16, v16, v17, vcc
	v_rsq_f32_e32 v16, v16
	s_nop 0
	v_mul_f32_e32 v17, 0x45800000, v16
	v_cndmask_b32_e32 v26, v16, v17, vcc
	v_pk_mul_f32 v[12:13], v[12:13], v[26:27] op_sel_hi:[1,0]
	v_pk_mul_f32 v[14:15], v[14:15], v[26:27] op_sel_hi:[1,0]
	v_pk_mul_f32 v[10:11], v[10:11], v[26:27] op_sel_hi:[1,0]
	v_pk_mul_f32 v[8:9], v[8:9], v[26:27] op_sel_hi:[1,0]
	v_pk_mul_f32 v[6:7], v[6:7], v[26:27] op_sel_hi:[1,0]
	v_pk_mul_f32 v[4:5], v[4:5], v[26:27] op_sel_hi:[1,0]
	v_pk_mul_f32 v[2:3], v[2:3], v[26:27] op_sel_hi:[1,0]
	v_pk_mul_f32 v[0:1], v[0:1], v[26:27] op_sel_hi:[1,0]
	v_pk_mul_f32 v[14:15], v[38:39], v[14:15]
	v_pk_mul_f32 v[12:13], v[36:37], v[12:13]
	global_store_dwordx4 v[24:25], v[12:15], off
	v_pk_mul_f32 v[8:9], v[40:41], v[8:9]
	v_pk_mul_f32 v[10:11], v[42:43], v[10:11]
	global_store_dwordx4 v[24:25], v[8:11], off offset:1024
	v_pk_mul_f32 v[4:5], v[44:45], v[4:5]
	v_pk_mul_f32 v[6:7], v[46:47], v[6:7]
	global_store_dwordx4 v[24:25], v[4:7], off offset:2048
	v_pk_mul_f32 v[0:1], v[48:49], v[0:1]
	v_pk_mul_f32 v[2:3], v[50:51], v[2:3]
	global_store_dwordx4 v[24:25], v[0:3], off offset:3072
	s_cbranch_scc0 .LBB0_18
